# speedup vs baseline: 1.0168x; 1.0012x over previous
;   __device__ __forceinline__ u16* vT_sb() const { return (u16*)(ws + 457 * MB); }
;   __device__ __forceinline__ u16* vT_sw() const { return (u16*)(ws + 489 * MB); }
; #define WAIT_V(n) asm volatile("s_waitcnt vmcnt(%0)" ::"n"(n) : "memory")
; template <int EPI> ...
;     ...
;         const int b = row0 >> 12, t = row0 & 4095;
;         u16* vb = sbv ? (p.vT_sb() + ((long)(b * 512 + (col0 - 1024))) * 4096 + t)
;                       : (p.vT_sw() + ((long)(b * 128 + (col0 - 2176))) * 4096 + t);
;         WAIT_V(0);
;         u16* vrow = vb - (fq * 4) * 4096L - fr;
; #pragma unroll
;         for (int hv = 0; hv < 2; ++hv) {
; #pragma unroll
;           for (int m = 0; m < 8; ++m)
; #pragma unroll
;             for (int nn = 0; nn < 2; ++nn)
; #pragma unroll
;               for (int j = 0; j < 4; ++j)
;                 *(u16*)(wst + (nn * 16 + fq * 4 + j) * 256 + (m * 16 + fr) * 2) =
;                     (u16)pack2(acc[m][hv * 2 + nn][j] * rs[m], 0.f);
.LBB0_124:
	s_movk_i32 s16, 0xf80
	s_add_u32 s6, s30, s6
	v_ashrrev_i32_e32 v153, 31, v152
	v_and_or_b32 v139, v139, s16, v147
	s_addc_u32 s7, s31, s7
	v_lshlrev_b64 v[152:153], 13, v[152:153]
	v_lshl_add_u64 v[152:153], s[6:7], 0, v[152:153]
	v_lshlrev_b32_e32 v172, 1, v139
	v_mov_b32_e32 v173, v2
	v_lshl_add_u64 v[152:153], v[152:153], 0, v[172:173]
	v_lshlrev_b32_e32 v139, 15, v145
	v_sub_co_u32_e32 v139, vcc, v152, v139
	v_lshlrev_b32_e32 v143, 1, v147
	s_nop 0
	v_subbrev_co_u32_e32 v141, vcc, 0, v153, vcc
	v_lshlrev_b32_e32 v172, 4, v147
	v_mul_f32_e32 v132, v132, v150
	v_lshlrev_b32_e32 v147, 10, v145
	v_mul_f32_e32 v128, v128, v150
	v_mul_f32_e32 v124, v124, v148
	v_mul_f32_e32 v116, v116, v148
	v_mul_f32_e32 v108, v108, v146
	v_mul_f32_e32 v100, v100, v146
	v_mul_f32_e32 v92, v92, v144
	v_mul_f32_e32 v84, v84, v144
	v_mul_f32_e32 v76, v76, v142
	v_mul_f32_e32 v68, v68, v142
	v_mul_f32_e32 v60, v60, v140
	v_mul_f32_e32 v56, v56, v140
	v_mul_f32_e32 v44, v44, v138
	v_mul_f32_e32 v40, v40, v138
	v_mul_f32_e32 v28, v28, v136
	v_mul_f32_e32 v24, v24, v136
	v_sub_co_u32_e32 v152, vcc, v139, v143
	v_add_u32_e32 v139, v137, v172
	v_cvt_pk_bf16_f32 v132, v132, s0
	v_add3_u32 v137, v137, v143, v147
	v_cvt_pk_bf16_f32 v128, v128, s0
	v_cvt_pk_bf16_f32 v124, v124, s0
	v_cvt_pk_bf16_f32 v116, v116, s0
	v_cvt_pk_bf16_f32 v108, v108, s0
	v_cvt_pk_bf16_f32 v100, v100, s0
	v_cvt_pk_bf16_f32 v92, v92, s0
	v_cvt_pk_bf16_f32 v84, v84, s0
	v_cvt_pk_bf16_f32 v76, v76, s0
	v_cvt_pk_bf16_f32 v68, v68, s0
	v_cvt_pk_bf16_f32 v60, v60, s0
	v_cvt_pk_bf16_f32 v56, v56, s0
	v_cvt_pk_bf16_f32 v44, v44, s0
	v_cvt_pk_bf16_f32 v40, v40, s0
	v_cvt_pk_bf16_f32 v28, v28, s0
	v_cvt_pk_bf16_f32 v24, v24, s0
	s_waitcnt vmcnt(0)
	ds_write_b16 v137, v132
	v_mul_f32_e32 v132, v133, v150
	ds_write_b16 v137, v128 offset:4096
	v_mul_f32_e32 v128, v129, v150
	ds_write_b16 v137, v124 offset:32
	v_mul_f32_e32 v124, v125, v148
	ds_write_b16 v137, v116 offset:4128
	v_mul_f32_e32 v116, v117, v148
	ds_write_b16 v137, v108 offset:64
	v_mul_f32_e32 v108, v109, v146
	ds_write_b16 v137, v100 offset:4160
	v_mul_f32_e32 v100, v101, v146
	ds_write_b16 v137, v92 offset:96
	v_mul_f32_e32 v92, v93, v144
	ds_write_b16 v137, v84 offset:4192
	v_mul_f32_e32 v84, v85, v144
	ds_write_b16 v137, v76 offset:128
	v_mul_f32_e32 v76, v77, v142
	ds_write_b16 v137, v68 offset:4224
	v_mul_f32_e32 v68, v69, v142
	ds_write_b16 v137, v60 offset:160
	v_mul_f32_e32 v60, v61, v140
	ds_write_b16 v137, v56 offset:4256
	v_mul_f32_e32 v56, v57, v140
	ds_write_b16 v137, v44 offset:192
	v_mul_f32_e32 v44, v45, v138
	ds_write_b16 v137, v40 offset:4288
	v_mul_f32_e32 v40, v41, v138
	ds_write_b16 v137, v28 offset:224
	v_mul_f32_e32 v28, v29, v136
	ds_write_b16 v137, v24 offset:4320
	v_mul_f32_e32 v24, v25, v136
	v_cvt_pk_bf16_f32 v132, v132, s0
	v_cvt_pk_bf16_f32 v128, v128, s0
	v_cvt_pk_bf16_f32 v124, v124, s0
	v_cvt_pk_bf16_f32 v116, v116, s0
	v_cvt_pk_bf16_f32 v108, v108, s0
	v_cvt_pk_bf16_f32 v100, v100, s0
	v_cvt_pk_bf16_f32 v92, v92, s0
	v_cvt_pk_bf16_f32 v84, v84, s0
	v_cvt_pk_bf16_f32 v76, v76, s0
	v_cvt_pk_bf16_f32 v68, v68, s0
	v_cvt_pk_bf16_f32 v60, v60, s0
	v_cvt_pk_bf16_f32 v56, v56, s0
	v_cvt_pk_bf16_f32 v44, v44, s0
	v_cvt_pk_bf16_f32 v40, v40, s0
	v_cvt_pk_bf16_f32 v28, v28, s0
	v_cvt_pk_bf16_f32 v24, v24, s0
	ds_write_b16 v137, v132 offset:256
	v_mul_f32_e32 v132, v134, v150
	ds_write_b16 v137, v128 offset:4352
	v_mul_f32_e32 v128, v130, v150
	ds_write_b16 v137, v124 offset:288
	v_mul_f32_e32 v124, v126, v148
	ds_write_b16 v137, v116 offset:4384
	v_mul_f32_e32 v116, v118, v148
	ds_write_b16 v137, v108 offset:320
	v_mul_f32_e32 v108, v110, v146
	ds_write_b16 v137, v100 offset:4416
	v_mul_f32_e32 v100, v102, v146
	ds_write_b16 v137, v92 offset:352
	v_mul_f32_e32 v92, v94, v144
	ds_write_b16 v137, v84 offset:4448
	v_mul_f32_e32 v84, v86, v144
	ds_write_b16 v137, v76 offset:384
	v_mul_f32_e32 v76, v78, v142
	ds_write_b16 v137, v68 offset:4480
	v_mul_f32_e32 v68, v70, v142
	ds_write_b16 v137, v60 offset:416
	v_mul_f32_e32 v60, v62, v140
	ds_write_b16 v137, v56 offset:4512
	v_mul_f32_e32 v56, v58, v140
	ds_write_b16 v137, v44 offset:448
	v_mul_f32_e32 v44, v46, v138
	ds_write_b16 v137, v40 offset:4544
	v_mul_f32_e32 v40, v42, v138
	ds_write_b16 v137, v28 offset:480
	v_mul_f32_e32 v28, v30, v136
	ds_write_b16 v137, v24 offset:4576
	v_mul_f32_e32 v24, v26, v136
	v_cvt_pk_bf16_f32 v132, v132, s0
	v_cvt_pk_bf16_f32 v128, v128, s0
	v_cvt_pk_bf16_f32 v124, v124, s0
	v_cvt_pk_bf16_f32 v116, v116, s0
	v_cvt_pk_bf16_f32 v108, v108, s0
	v_cvt_pk_bf16_f32 v100, v100, s0
	v_cvt_pk_bf16_f32 v92, v92, s0
	v_cvt_pk_bf16_f32 v84, v84, s0
	v_cvt_pk_bf16_f32 v76, v76, s0
	v_cvt_pk_bf16_f32 v68, v68, s0
	v_cvt_pk_bf16_f32 v60, v60, s0
	v_cvt_pk_bf16_f32 v56, v56, s0
	v_cvt_pk_bf16_f32 v44, v44, s0
	v_cvt_pk_bf16_f32 v40, v40, s0
	v_cvt_pk_bf16_f32 v28, v28, s0
	v_cvt_pk_bf16_f32 v24, v24, s0
	ds_write_b16 v137, v132 offset:512
	v_mul_f32_e32 v132, v135, v150
	ds_write_b16 v137, v128 offset:4608
	v_mul_f32_e32 v128, v131, v150
	ds_write_b16 v137, v124 offset:544
	v_mul_f32_e32 v124, v127, v148
	ds_write_b16 v137, v116 offset:4640
	v_mul_f32_e32 v116, v119, v148
	ds_write_b16 v137, v108 offset:576
	v_mul_f32_e32 v108, v111, v146
	ds_write_b16 v137, v100 offset:4672
	v_mul_f32_e32 v100, v103, v146
	ds_write_b16 v137, v92 offset:608
	v_mul_f32_e32 v92, v95, v144
	ds_write_b16 v137, v84 offset:4704
	v_mul_f32_e32 v84, v87, v144
	ds_write_b16 v137, v76 offset:640
	v_mul_f32_e32 v76, v79, v142
	ds_write_b16 v137, v68 offset:4736
	v_mul_f32_e32 v68, v71, v142
	ds_write_b16 v137, v60 offset:672
	v_mul_f32_e32 v60, v63, v140
; #define LDS_FENCE() asm volatile("s_waitcnt lgkmcnt(0)" ::: "memory")
; template <int EPI> ...
;     ...
;                 *(u16*)(wst + (nn * 16 + fq * 4 + j) * 256 + (m * 16 + fr) * 2) =
;                     (u16)pack2(acc[m][hv * 2 + nn][j] * rs[m], 0.f);
;           LDS_FENCE();
; #pragma unroll
;           for (int i = 0; i < 8; ++i) {
;             const int idx = i * 64 + lane, dvl = idx >> 4, ch = idx & 15;
;             const u32x4 d = *(const u32x4*)(wst + dvl * 256 + ch * 16);
;             *(u32x4*)(vrow + (long)(hv * 32 + dvl) * 4096 + ch * 8) = d;
;           }
;           LDS_FENCE();
	ds_write_b16 v137, v56 offset:4768
	v_mul_f32_e32 v56, v59, v140
	ds_write_b16 v137, v44 offset:704
	v_mul_f32_e32 v44, v47, v138
	ds_write_b16 v137, v40 offset:4800
	v_mul_f32_e32 v40, v43, v138
	ds_write_b16 v137, v28 offset:736
	v_mul_f32_e32 v28, v31, v136
	ds_write_b16 v137, v24 offset:4832
	v_mul_f32_e32 v24, v27, v136
	v_cvt_pk_bf16_f32 v132, v132, s0
	v_cvt_pk_bf16_f32 v128, v128, s0
	v_cvt_pk_bf16_f32 v124, v124, s0
	v_cvt_pk_bf16_f32 v116, v116, s0
	v_cvt_pk_bf16_f32 v108, v108, s0
	v_cvt_pk_bf16_f32 v100, v100, s0
	v_cvt_pk_bf16_f32 v92, v92, s0
	v_cvt_pk_bf16_f32 v84, v84, s0
	v_cvt_pk_bf16_f32 v76, v76, s0
	v_cvt_pk_bf16_f32 v68, v68, s0
	v_cvt_pk_bf16_f32 v60, v60, s0
	v_cvt_pk_bf16_f32 v56, v56, s0
	v_cvt_pk_bf16_f32 v44, v44, s0
	v_cvt_pk_bf16_f32 v40, v40, s0
	v_cvt_pk_bf16_f32 v28, v28, s0
	v_cvt_pk_bf16_f32 v24, v24, s0
	ds_write_b16 v137, v132 offset:768
	ds_write_b16 v137, v128 offset:4864
	ds_write_b16 v137, v124 offset:800
	ds_write_b16 v137, v116 offset:4896
	ds_write_b16 v137, v108 offset:832
	ds_write_b16 v137, v100 offset:4928
	ds_write_b16 v137, v92 offset:864
	ds_write_b16 v137, v84 offset:4960
	ds_write_b16 v137, v76 offset:896
	ds_write_b16 v137, v68 offset:4992
	ds_write_b16 v137, v60 offset:928
	ds_write_b16 v137, v56 offset:5024
	ds_write_b16 v137, v44 offset:960
	ds_write_b16 v137, v40 offset:5056
	ds_write_b16 v137, v28 offset:992
	ds_write_b16 v137, v24 offset:5088
	v_subbrev_co_u32_e32 v153, vcc, 0, v141, vcc
	v_lshl_add_u32 v141, v145, 8, v139
	s_waitcnt lgkmcnt(0)
	ds_read_b128 v[26:29], v141
	v_or_b32_e32 v30, 4, v145
	v_lshl_add_u32 v62, v30, 8, v139
	ds_read_b128 v[40:43], v62
	v_lshl_add_u64 v[152:153], v[152:153], 0, v[172:173]
	v_lshlrev_b32_e32 v24, 13, v145
	v_mov_b32_e32 v25, v2
	v_lshl_add_u64 v[24:25], v[152:153], 0, v[24:25]
	s_waitcnt lgkmcnt(0)
	global_store_dwordx4 v[24:25], v[26:29], off nt
	v_or_b32_e32 v46, 12, v145
	v_lshl_add_u32 v68, v46, 8, v139
	v_lshlrev_b32_e32 v26, 13, v30
	v_mov_b32_e32 v27, v2
	v_lshl_add_u64 v[26:27], v[152:153], 0, v[26:27]
	global_store_dwordx4 v[26:27], v[40:43], off nt
	v_or_b32_e32 v58, 20, v145
	v_lshl_add_u32 v70, v58, 8, v139
	v_or_b32_e32 v40, 8, v145
	v_lshl_add_u32 v63, v40, 8, v139
	ds_read_b128 v[28:31], v63
	v_lshlrev_b32_e32 v40, 13, v40
	v_mov_b32_e32 v41, v2
	v_lshl_add_u64 v[44:45], v[152:153], 0, v[40:41]
	ds_read_b128 v[40:43], v68
	s_waitcnt lgkmcnt(1)
	global_store_dwordx4 v[44:45], v[28:31], off nt
	v_or_b32_e32 v76, 28, v145
	v_lshl_add_u32 v77, v76, 8, v139
	v_lshlrev_b32_e32 v28, 13, v46
	v_mov_b32_e32 v29, v2
	v_lshl_add_u64 v[46:47], v[152:153], 0, v[28:29]
	s_waitcnt lgkmcnt(0)
	global_store_dwordx4 v[46:47], v[40:43], off nt
	v_mul_f32_e32 v20, v20, v138
	v_mul_f32_e32 v16, v16, v138
	v_or_b32_e32 v40, 16, v145
	v_lshl_add_u32 v69, v40, 8, v139
	ds_read_b128 v[28:31], v69
	v_lshlrev_b32_e32 v40, 13, v40
	v_mov_b32_e32 v41, v2
	v_lshl_add_u64 v[56:57], v[152:153], 0, v[40:41]
	ds_read_b128 v[40:43], v70
	s_waitcnt lgkmcnt(1)
	global_store_dwordx4 v[56:57], v[28:31], off nt
	v_mul_f32_e32 v12, v12, v136
	v_mul_f32_e32 v8, v8, v136
	v_lshlrev_b32_e32 v28, 13, v58
	v_mov_b32_e32 v29, v2
	v_lshl_add_u64 v[58:59], v[152:153], 0, v[28:29]
	s_waitcnt lgkmcnt(0)
	global_store_dwordx4 v[58:59], v[40:43], off nt
	v_cvt_pk_bf16_f32 v20, v20, s0
	v_cvt_pk_bf16_f32 v16, v16, s0
	v_or_b32_e32 v40, 24, v145
	v_lshl_add_u32 v71, v40, 8, v139
	ds_read_b128 v[28:31], v71
	v_lshlrev_b32_e32 v40, 13, v40
	v_mov_b32_e32 v41, v2
	v_lshl_add_u64 v[60:61], v[152:153], 0, v[40:41]
	ds_read_b128 v[40:43], v77
	s_waitcnt lgkmcnt(1)
	global_store_dwordx4 v[60:61], v[28:31], off nt
	v_cvt_pk_bf16_f32 v12, v12, s0
	v_cvt_pk_bf16_f32 v8, v8, s0
	v_lshlrev_b32_e32 v28, 13, v76
	v_mov_b32_e32 v29, v2
	v_lshl_add_u64 v[28:29], v[152:153], 0, v[28:29]
	v_mul_f32_e32 v30, v120, v150
	s_waitcnt lgkmcnt(0)
	global_store_dwordx4 v[28:29], v[40:43], off nt
	v_cvt_pk_bf16_f32 v30, v30, s0
	s_waitcnt lgkmcnt(0)
	ds_write_b16 v137, v30
	v_mul_f32_e32 v30, v121, v150
	v_cvt_pk_bf16_f32 v30, v30, s0
	ds_write_b16 v137, v30 offset:256
	v_mul_f32_e32 v30, v122, v150
	v_cvt_pk_bf16_f32 v30, v30, s0
	ds_write_b16 v137, v30 offset:512
	v_mul_f32_e32 v30, v123, v150
	v_cvt_pk_bf16_f32 v30, v30, s0
	ds_write_b16 v137, v30 offset:768
	v_mul_f32_e32 v30, v112, v150
	v_cvt_pk_bf16_f32 v30, v30, s0
	ds_write_b16 v137, v30 offset:4096
	v_mul_f32_e32 v30, v113, v150
	v_cvt_pk_bf16_f32 v30, v30, s0
	ds_write_b16 v137, v30 offset:4352
	v_mul_f32_e32 v30, v114, v150
	v_cvt_pk_bf16_f32 v30, v30, s0
	ds_write_b16 v137, v30 offset:4608
	v_mul_f32_e32 v30, v115, v150
	v_cvt_pk_bf16_f32 v30, v30, s0
	ds_write_b16 v137, v30 offset:4864
	v_mul_f32_e32 v30, v104, v148
	v_cvt_pk_bf16_f32 v30, v30, s0
	ds_write_b16 v137, v30 offset:32
	v_mul_f32_e32 v30, v105, v148
	v_cvt_pk_bf16_f32 v30, v30, s0
	ds_write_b16 v137, v30 offset:288
	v_mul_f32_e32 v30, v106, v148
	v_cvt_pk_bf16_f32 v30, v30, s0
	ds_write_b16 v137, v30 offset:544
	v_mul_f32_e32 v30, v107, v148
	v_cvt_pk_bf16_f32 v30, v30, s0
	ds_write_b16 v137, v30 offset:800
	v_mul_f32_e32 v30, v96, v148
	v_cvt_pk_bf16_f32 v30, v30, s0
	ds_write_b16 v137, v30 offset:4128
	v_mul_f32_e32 v30, v97, v148
	v_cvt_pk_bf16_f32 v30, v30, s0
	ds_write_b16 v137, v30 offset:4384
	v_mul_f32_e32 v30, v98, v148
	v_cvt_pk_bf16_f32 v30, v30, s0
	ds_write_b16 v137, v30 offset:4640
	v_mul_f32_e32 v30, v99, v148
	v_cvt_pk_bf16_f32 v30, v30, s0
	ds_write_b16 v137, v30 offset:4896
	v_mul_f32_e32 v30, v88, v146
	v_cvt_pk_bf16_f32 v30, v30, s0
	ds_write_b16 v137, v30 offset:64
	v_mul_f32_e32 v30, v89, v146
	v_cvt_pk_bf16_f32 v30, v30, s0
	ds_write_b16 v137, v30 offset:320
; #define LDS_FENCE() asm volatile("s_waitcnt lgkmcnt(0)" ::: "memory")
; template <int EPI> ...
;     ...
;                 *(u16*)(wst + (nn * 16 + fq * 4 + j) * 256 + (m * 16 + fr) * 2) =
;                     (u16)pack2(acc[m][hv * 2 + nn][j] * rs[m], 0.f);
;           LDS_FENCE();
; #pragma unroll
;           for (int i = 0; i < 8; ++i) {
;             const int idx = i * 64 + lane, dvl = idx >> 4, ch = idx & 15;
;             const u32x4 d = *(const u32x4*)(wst + dvl * 256 + ch * 16);
;             *(u32x4*)(vrow + (long)(hv * 32 + dvl) * 4096 + ch * 8) = d;
;           }
;           LDS_FENCE();
	v_mul_f32_e32 v30, v90, v146
	v_cvt_pk_bf16_f32 v30, v30, s0
	ds_write_b16 v137, v30 offset:576
	v_mul_f32_e32 v30, v91, v146
	v_cvt_pk_bf16_f32 v30, v30, s0
	ds_write_b16 v137, v30 offset:832
	v_mul_f32_e32 v30, v80, v146
	v_cvt_pk_bf16_f32 v30, v30, s0
	ds_write_b16 v137, v30 offset:4160
	v_mul_f32_e32 v30, v81, v146
	v_cvt_pk_bf16_f32 v30, v30, s0
	ds_write_b16 v137, v30 offset:4416
	v_mul_f32_e32 v30, v82, v146
	v_cvt_pk_bf16_f32 v30, v30, s0
	ds_write_b16 v137, v30 offset:4672
	v_mul_f32_e32 v30, v83, v146
	v_cvt_pk_bf16_f32 v30, v30, s0
	ds_write_b16 v137, v30 offset:4928
	v_mul_f32_e32 v30, v72, v144
	v_cvt_pk_bf16_f32 v30, v30, s0
	ds_write_b16 v137, v30 offset:96
	v_mul_f32_e32 v30, v73, v144
	v_cvt_pk_bf16_f32 v30, v30, s0
	ds_write_b16 v137, v30 offset:352
	v_mul_f32_e32 v30, v74, v144
	v_cvt_pk_bf16_f32 v30, v30, s0
	ds_write_b16 v137, v30 offset:608
	v_mul_f32_e32 v30, v75, v144
	v_cvt_pk_bf16_f32 v30, v30, s0
	ds_write_b16 v137, v30 offset:864
	v_mul_f32_e32 v30, v64, v144
	v_cvt_pk_bf16_f32 v30, v30, s0
	ds_write_b16 v137, v30 offset:4192
	v_mul_f32_e32 v30, v65, v144
	v_cvt_pk_bf16_f32 v30, v30, s0
	ds_write_b16 v137, v30 offset:4448
	v_mul_f32_e32 v30, v66, v144
	v_cvt_pk_bf16_f32 v30, v30, s0
	ds_write_b16 v137, v30 offset:4704
	v_mul_f32_e32 v30, v67, v144
	v_cvt_pk_bf16_f32 v30, v30, s0
	ds_write_b16 v137, v30 offset:4960
	v_mul_f32_e32 v30, v52, v142
	v_cvt_pk_bf16_f32 v30, v30, s0
	ds_write_b16 v137, v30 offset:128
	v_mul_f32_e32 v30, v53, v142
	v_cvt_pk_bf16_f32 v30, v30, s0
	ds_write_b16 v137, v30 offset:384
	v_mul_f32_e32 v30, v54, v142
	v_cvt_pk_bf16_f32 v30, v30, s0
	ds_write_b16 v137, v30 offset:640
	v_mul_f32_e32 v30, v55, v142
	v_cvt_pk_bf16_f32 v30, v30, s0
	ds_write_b16 v137, v30 offset:896
	v_mul_f32_e32 v30, v48, v142
	v_cvt_pk_bf16_f32 v30, v30, s0
	ds_write_b16 v137, v30 offset:4224
	v_mul_f32_e32 v30, v49, v142
	v_cvt_pk_bf16_f32 v30, v30, s0
	ds_write_b16 v137, v30 offset:4480
	v_mul_f32_e32 v30, v50, v142
	v_cvt_pk_bf16_f32 v30, v30, s0
	ds_write_b16 v137, v30 offset:4736
	v_mul_f32_e32 v30, v51, v142
	v_cvt_pk_bf16_f32 v30, v30, s0
	ds_write_b16 v137, v30 offset:4992
	v_mul_f32_e32 v30, v36, v140
	v_cvt_pk_bf16_f32 v30, v30, s0
	ds_write_b16 v137, v30 offset:160
	v_mul_f32_e32 v30, v37, v140
	v_cvt_pk_bf16_f32 v30, v30, s0
	ds_write_b16 v137, v30 offset:416
	v_mul_f32_e32 v30, v38, v140
	v_cvt_pk_bf16_f32 v30, v30, s0
	ds_write_b16 v137, v30 offset:672
	v_mul_f32_e32 v30, v39, v140
	v_cvt_pk_bf16_f32 v30, v30, s0
	ds_write_b16 v137, v30 offset:928
	v_mul_f32_e32 v30, v32, v140
	v_cvt_pk_bf16_f32 v30, v30, s0
	ds_write_b16 v137, v30 offset:4256
	v_mul_f32_e32 v30, v33, v140
	ds_write_b16 v137, v20 offset:192
	v_mul_f32_e32 v20, v21, v138
	ds_write_b16 v137, v16 offset:4288
	v_mul_f32_e32 v16, v17, v138
	ds_write_b16 v137, v12 offset:224
	v_mul_f32_e32 v12, v13, v136
	ds_write_b16 v137, v8 offset:4320
	v_mul_f32_e32 v8, v9, v136
	v_cvt_pk_bf16_f32 v30, v30, s0
	v_cvt_pk_bf16_f32 v20, v20, s0
	v_cvt_pk_bf16_f32 v16, v16, s0
	v_cvt_pk_bf16_f32 v12, v12, s0
	v_cvt_pk_bf16_f32 v8, v8, s0
	ds_write_b16 v137, v30 offset:4512
	v_mul_f32_e32 v30, v34, v140
	ds_write_b16 v137, v20 offset:448
	v_mul_f32_e32 v20, v22, v138
	ds_write_b16 v137, v16 offset:4544
	v_mul_f32_e32 v16, v18, v138
	ds_write_b16 v137, v12 offset:480
	v_mul_f32_e32 v12, v14, v136
	ds_write_b16 v137, v8 offset:4576
	v_mul_f32_e32 v8, v10, v136
	v_cvt_pk_bf16_f32 v30, v30, s0
	v_cvt_pk_bf16_f32 v20, v20, s0
	v_cvt_pk_bf16_f32 v16, v16, s0
	v_cvt_pk_bf16_f32 v12, v12, s0
	v_cvt_pk_bf16_f32 v8, v8, s0
	ds_write_b16 v137, v30 offset:4768
	v_mul_f32_e32 v30, v35, v140
	ds_write_b16 v137, v20 offset:704
	v_mul_f32_e32 v20, v23, v138
	ds_write_b16 v137, v16 offset:4800
	v_mul_f32_e32 v16, v19, v138
	ds_write_b16 v137, v12 offset:736
	v_mul_f32_e32 v12, v15, v136
	ds_write_b16 v137, v8 offset:4832
	v_mul_f32_e32 v8, v11, v136
	v_cvt_pk_bf16_f32 v30, v30, s0
	v_cvt_pk_bf16_f32 v20, v20, s0
	v_cvt_pk_bf16_f32 v16, v16, s0
	v_cvt_pk_bf16_f32 v12, v12, s0
	v_cvt_pk_bf16_f32 v8, v8, s0
	ds_write_b16 v137, v30 offset:5024
	ds_write_b16 v137, v20 offset:960
	ds_write_b16 v137, v16 offset:5056
	ds_write_b16 v137, v12 offset:992
	ds_write_b16 v137, v8 offset:5088
	s_waitcnt lgkmcnt(0)
	ds_read_b128 v[8:11], v141
	ds_read_b128 v[12:15], v62
	v_add_co_u32_e32 v16, vcc, s89, v24
	s_nop 1
	v_addc_co_u32_e32 v17, vcc, 0, v25, vcc
	s_waitcnt lgkmcnt(1)
	global_store_dwordx4 v[16:17], v[8:11], off nt
	s_nop 1
	v_add_co_u32_e32 v8, vcc, s89, v26
	s_nop 1
	v_addc_co_u32_e32 v9, vcc, 0, v27, vcc
	s_waitcnt lgkmcnt(0)
	global_store_dwordx4 v[8:9], v[12:15], off nt
	ds_read_b128 v[8:11], v63
	ds_read_b128 v[12:15], v68
	v_add_co_u32_e32 v16, vcc, s89, v44
	s_nop 1
	v_addc_co_u32_e32 v17, vcc, 0, v45, vcc
	s_waitcnt lgkmcnt(1)
	global_store_dwordx4 v[16:17], v[8:11], off nt
	s_nop 1
	v_add_co_u32_e32 v8, vcc, s89, v46
	s_nop 1
	v_addc_co_u32_e32 v9, vcc, 0, v47, vcc
	s_waitcnt lgkmcnt(0)
	global_store_dwordx4 v[8:9], v[12:15], off nt
	ds_read_b128 v[8:11], v69
	ds_read_b128 v[12:15], v70
	v_add_co_u32_e32 v16, vcc, s89, v56
	s_nop 1
	v_addc_co_u32_e32 v17, vcc, 0, v57, vcc
	s_waitcnt lgkmcnt(1)
	global_store_dwordx4 v[16:17], v[8:11], off nt
	s_nop 1
	v_add_co_u32_e32 v8, vcc, s89, v58
	s_nop 1
	v_addc_co_u32_e32 v9, vcc, 0, v59, vcc
	s_waitcnt lgkmcnt(0)
	global_store_dwordx4 v[8:9], v[12:15], off nt
	ds_read_b128 v[8:11], v71
	ds_read_b128 v[12:15], v77
	v_add_co_u32_e32 v16, vcc, 0x40000, v60
	s_nop 1
	v_addc_co_u32_e32 v17, vcc, 0, v61, vcc
	s_waitcnt lgkmcnt(1)
	global_store_dwordx4 v[16:17], v[8:11], off nt
	s_nop 1
	v_add_co_u32_e32 v8, vcc, 0x40000, v28
	s_nop 1
	v_addc_co_u32_e32 v9, vcc, 0, v29, vcc
	s_waitcnt lgkmcnt(0)
	global_store_dwordx4 v[8:9], v[12:15], off nt
	s_waitcnt lgkmcnt(0)
